# in-proj gate epilogue regenerated: packed ops, ratios paired with v_permlane16_swap so 16 dwordx4 stores replace 32 dwordx2
# speedup vs baseline: 1.0043x; 1.0043x over previous
; __device__ __forceinline__ unsigned cvt_pk_bf16(float lo, float hi) { const f32x2_t f = {lo, hi}; const bf16x2_t b = __builtin_convertvector(f, bf16x2_t); unsigned r; __builtin_memcpy(&r, &b, 4); return r; }
;     __device__ __forceinline__ void operator()(const Acc& acc, const Unit& u, int wr, int wc, int fr, int fq) const {
;     ...
;         if (pn >= 24) {
;             const int ch0 = (pn - 24) * 64 + wc * 16 + fq * 4;
;             f32x4 bgv[4];
; #pragma unroll
;             for (int br = 0; br < 4; ++br) bgv[br] = *(const f32x4*)(bgate + br * DM + ch0);
; #pragma unroll
;             for (int ai = 0; ai < 2; ++ai)
; #pragma unroll
;                 for (int m = 0; m < 4; ++m) { const int row = row0 + ai * 128 + m * 16; f32x4 g[4], d[4];
;                     const int cl = ch0 & 255, rl = row & 255;
;                     const size_t roff = ((((((size_t)((row >> 8) * 8 + (ch0 >> 8)) * 2 + (rl >> 7)) * 4 + ((rl >> 4) & 3)) * 2 + (cl >> 7)) * 8 + (((rl >> 6) & 1) * 4 + ((cl >> 5) & 3))) * 64
;                                          + ((rl & 15) + 16 * ((cl >> 3) & 3))) * 8 + (cl & 7);
; #pragma unroll
;                     for (int br = 0; br < 4; ++br)
; #pragma unroll
;                         for (int j = 0; j < 4; ++j) { d[br][j] = fminf(1.0f + __builtin_amdgcn_exp2f(-1.4426950408889634f * (acc[ai][br >> 1][m][br & 1][j] + bgv[br][j])), 1e30f); g[br][j] = __builtin_amdgcn_rcpf(d[br][j]); }
; #pragma unroll
;                     for (int k = 0; k < 4; ++k) { f32x4 r = g[k];
;                         if (k < 3) {
; #pragma unroll
;                             for (int j = 0; j < 4; ++j) r[j] = g[k][j] * d[k + 1][j]; }
;                         uint2 w; w.x = cvt_pk_bf16(r[0], r[1]); w.y = cvt_pk_bf16(r[2], r[3]);
;                         *(uint2*)(R + (size_t)k * T * DM + roff) = w; } }
.LBB0_721:
	s_and_b64 vcc, exec, s[6:7]
	s_cbranch_vccz .LBB0_723
	s_lshl_b32 s6, s4, 6
	s_addk_i32 s6, 0xfa00
	v_readlane_b32 s8, v249, 63
	v_or_b32_e32 v162, s6, v211
	v_readlane_b32 s9, v248, 0
	v_lshrrev_b32_e32 v159, 5, v162
	s_lshl_b32 s4, s4, 2
	v_lshl_add_u64 v[132:133], v[162:163], 2, s[8:9]
	v_add_co_u32_e32 v134, vcc, 0x2000, v132
	global_load_dwordx4 v[128:131], v[132:133], off
	s_nop 0
	v_addc_co_u32_e32 v135, vcc, 0, v133, vcc
	global_load_dwordx4 v[140:143], v[134:135], off
	v_add_co_u32_e32 v134, vcc, 0x4000, v132
	s_lshr_b32 s8, s6, 8
	s_nop 0
	v_addc_co_u32_e32 v135, vcc, 0, v133, vcc
	global_load_dwordx4 v[136:139], v[134:135], off
	v_add_co_u32_e32 v132, vcc, s52, v132
	v_readlane_b32 s6, v248, 11
	s_nop 0
	v_addc_co_u32_e32 v133, vcc, 0, v133, vcc
	global_load_dwordx4 v[132:135], v[132:133], off
	v_and_or_b32 v159, v159, 3, s6
	v_and_or_b32 v159, s4, 8, v159
	s_ashr_i32 s4, s51, 5
	s_and_b32 s4, s4, -8
	s_add_i32 s6, s4, s8
	s_ashr_i32 s7, s6, 31
	v_readlane_b32 s10, v248, 12
	s_lshl_b64 s[6:7], s[6:7], 17
	v_readlane_b32 s11, v248, 13
	s_or_b64 s[6:7], s[6:7], s[10:11]
	s_add_u32 s10, s20, s6
	s_addc_u32 s11, s21, s7
	v_mov_b32_e32 v167, v163
	s_waitcnt vmcnt(0)
	v_lshlrev_b32_e32 v162, 10, v159
	v_mov_b32_e32 v159, v163
	s_mov_b32 s8, 0xbfb8aa3b
	v_lshl_add_u64 v[168:169], v[162:163], 0, v[158:159]
	v_lshl_add_u64 v[168:169], v[168:169], 0, v[166:167]
	v_bfe_u32 v170, v198, 4, 1
	v_mul_u32_u24_e32 v170, 0x3ff8, v170
	v_mov_b32_e32 v171, v163
	v_lshl_add_u64 v[168:169], v[168:169], 0, v[170:171]
	v_pk_add_f32 v[214:215], v[120:121], v[128:129]
	v_pk_add_f32 v[216:217], v[122:123], v[130:131]
	v_pk_add_f32 v[218:219], v[124:125], v[140:141]
	v_pk_add_f32 v[220:221], v[126:127], v[142:143]
	v_pk_add_f32 v[222:223], v[116:117], v[136:137]
	v_pk_add_f32 v[224:225], v[118:119], v[138:139]
	v_pk_add_f32 v[226:227], v[112:113], v[132:133]
	v_pk_add_f32 v[228:229], v[114:115], v[134:135]
	v_pk_mul_f32 v[214:215], v[214:215], s[8:9] op_sel_hi:[1,0]
	v_pk_mul_f32 v[216:217], v[216:217], s[8:9] op_sel_hi:[1,0]
	v_pk_mul_f32 v[218:219], v[218:219], s[8:9] op_sel_hi:[1,0]
	v_pk_mul_f32 v[220:221], v[220:221], s[8:9] op_sel_hi:[1,0]
	v_pk_mul_f32 v[222:223], v[222:223], s[8:9] op_sel_hi:[1,0]
	v_pk_mul_f32 v[224:225], v[224:225], s[8:9] op_sel_hi:[1,0]
	v_pk_mul_f32 v[226:227], v[226:227], s[8:9] op_sel_hi:[1,0]
	v_pk_mul_f32 v[228:229], v[228:229], s[8:9] op_sel_hi:[1,0]
	v_exp_f32_e32 v214, v214
	v_exp_f32_e32 v215, v215
	v_exp_f32_e32 v216, v216
	v_exp_f32_e32 v217, v217
	v_exp_f32_e32 v218, v218
	v_exp_f32_e32 v219, v219
	v_exp_f32_e32 v220, v220
	v_exp_f32_e32 v221, v221
	v_exp_f32_e32 v222, v222
	v_exp_f32_e32 v223, v223
	v_exp_f32_e32 v224, v224
	v_exp_f32_e32 v225, v225
	v_exp_f32_e32 v226, v226
	v_exp_f32_e32 v227, v227
	v_exp_f32_e32 v228, v228
	v_exp_f32_e32 v229, v229
	v_pk_add_f32 v[214:215], v[214:215], 1.0 op_sel_hi:[1,0]
	v_pk_add_f32 v[216:217], v[216:217], 1.0 op_sel_hi:[1,0]
	v_pk_add_f32 v[218:219], v[218:219], 1.0 op_sel_hi:[1,0]
	v_pk_add_f32 v[220:221], v[220:221], 1.0 op_sel_hi:[1,0]
	v_pk_add_f32 v[222:223], v[222:223], 1.0 op_sel_hi:[1,0]
	v_pk_add_f32 v[224:225], v[224:225], 1.0 op_sel_hi:[1,0]
	v_pk_add_f32 v[226:227], v[226:227], 1.0 op_sel_hi:[1,0]
	v_pk_add_f32 v[228:229], v[228:229], 1.0 op_sel_hi:[1,0]
	v_min_f32_e32 v214, 0x7149f2ca, v214
	v_min_f32_e32 v215, 0x7149f2ca, v215
	v_min_f32_e32 v216, 0x7149f2ca, v216
	v_min_f32_e32 v217, 0x7149f2ca, v217
	v_min_f32_e32 v218, 0x7149f2ca, v218
	v_min_f32_e32 v219, 0x7149f2ca, v219
	v_min_f32_e32 v220, 0x7149f2ca, v220
	v_min_f32_e32 v221, 0x7149f2ca, v221
	v_min_f32_e32 v222, 0x7149f2ca, v222
	v_min_f32_e32 v223, 0x7149f2ca, v223
	v_min_f32_e32 v224, 0x7149f2ca, v224
	v_min_f32_e32 v225, 0x7149f2ca, v225
	v_min_f32_e32 v226, 0x7149f2ca, v226
	v_min_f32_e32 v227, 0x7149f2ca, v227
	v_min_f32_e32 v228, 0x7149f2ca, v228
	v_min_f32_e32 v229, 0x7149f2ca, v229
	v_rcp_f32_e32 v230, v214
	v_rcp_f32_e32 v231, v215
	v_rcp_f32_e32 v232, v216
	v_rcp_f32_e32 v233, v217
	v_rcp_f32_e32 v234, v218
	v_rcp_f32_e32 v235, v219
	v_rcp_f32_e32 v236, v220
	v_rcp_f32_e32 v237, v221
	v_rcp_f32_e32 v238, v222
	v_rcp_f32_e32 v239, v223
	v_rcp_f32_e32 v240, v224
	v_rcp_f32_e32 v241, v225
	v_rcp_f32_e32 v242, v226
	v_rcp_f32_e32 v243, v227
	v_rcp_f32_e32 v244, v228
	v_rcp_f32_e32 v245, v229
	v_pk_mul_f32 v[230:231], v[230:231], v[218:219]
	v_pk_mul_f32 v[232:233], v[232:233], v[220:221]
	v_pk_mul_f32 v[234:235], v[234:235], v[222:223]
	v_pk_mul_f32 v[236:237], v[236:237], v[224:225]
	v_pk_mul_f32 v[238:239], v[238:239], v[226:227]
	v_pk_mul_f32 v[240:241], v[240:241], v[228:229]
	v_cvt_pk_bf16_f32 v172, v230, v231
	v_cvt_pk_bf16_f32 v173, v232, v233
	v_cvt_pk_bf16_f32 v176, v234, v235
	v_cvt_pk_bf16_f32 v177, v236, v237
	v_cvt_pk_bf16_f32 v180, v238, v239
	v_cvt_pk_bf16_f32 v181, v240, v241
	v_cvt_pk_bf16_f32 v184, v242, v243
	v_cvt_pk_bf16_f32 v185, v244, v245
	v_pk_add_f32 v[214:215], v[108:109], v[128:129]
	v_pk_add_f32 v[216:217], v[110:111], v[130:131]
	v_pk_add_f32 v[218:219], v[104:105], v[140:141]
	v_pk_add_f32 v[220:221], v[106:107], v[142:143]
	v_pk_add_f32 v[222:223], v[100:101], v[136:137]
	v_pk_add_f32 v[224:225], v[102:103], v[138:139]
	v_pk_add_f32 v[226:227], v[96:97], v[132:133]
	v_pk_add_f32 v[228:229], v[98:99], v[134:135]
	v_pk_mul_f32 v[214:215], v[214:215], s[8:9] op_sel_hi:[1,0]
	v_pk_mul_f32 v[216:217], v[216:217], s[8:9] op_sel_hi:[1,0]
	v_pk_mul_f32 v[218:219], v[218:219], s[8:9] op_sel_hi:[1,0]
	v_pk_mul_f32 v[220:221], v[220:221], s[8:9] op_sel_hi:[1,0]
	v_pk_mul_f32 v[222:223], v[222:223], s[8:9] op_sel_hi:[1,0]
	v_pk_mul_f32 v[224:225], v[224:225], s[8:9] op_sel_hi:[1,0]
; __device__ __forceinline__ unsigned cvt_pk_bf16(float lo, float hi) { const f32x2_t f = {lo, hi}; const bf16x2_t b = __builtin_convertvector(f, bf16x2_t); unsigned r; __builtin_memcpy(&r, &b, 4); return r; }
;     __device__ __forceinline__ void operator()(const Acc& acc, const Unit& u, int wr, int wc, int fr, int fq) const {
;     ...
;             for (int ai = 0; ai < 2; ++ai)
; #pragma unroll
;                 for (int m = 0; m < 4; ++m) { const int row = row0 + ai * 128 + m * 16; f32x4 g[4], d[4];
;                     const int cl = ch0 & 255, rl = row & 255;
;                     const size_t roff = ((((((size_t)((row >> 8) * 8 + (ch0 >> 8)) * 2 + (rl >> 7)) * 4 + ((rl >> 4) & 3)) * 2 + (cl >> 7)) * 8 + (((rl >> 6) & 1) * 4 + ((cl >> 5) & 3))) * 64
;                                          + ((rl & 15) + 16 * ((cl >> 3) & 3))) * 8 + (cl & 7);
; #pragma unroll
;                     for (int br = 0; br < 4; ++br)
; #pragma unroll
;                         for (int j = 0; j < 4; ++j) { d[br][j] = fminf(1.0f + __builtin_amdgcn_exp2f(-1.4426950408889634f * (acc[ai][br >> 1][m][br & 1][j] + bgv[br][j])), 1e30f); g[br][j] = __builtin_amdgcn_rcpf(d[br][j]); }
; #pragma unroll
;                     for (int k = 0; k < 4; ++k) { f32x4 r = g[k];
;                         if (k < 3) {
; #pragma unroll
;                             for (int j = 0; j < 4; ++j) r[j] = g[k][j] * d[k + 1][j]; }
;                         uint2 w; w.x = cvt_pk_bf16(r[0], r[1]); w.y = cvt_pk_bf16(r[2], r[3]);
;                         *(uint2*)(R + (size_t)k * T * DM + roff) = w; } }
	v_pk_mul_f32 v[226:227], v[226:227], s[8:9] op_sel_hi:[1,0]
	v_pk_mul_f32 v[228:229], v[228:229], s[8:9] op_sel_hi:[1,0]
	v_exp_f32_e32 v214, v214
	v_exp_f32_e32 v215, v215
	v_exp_f32_e32 v216, v216
	v_exp_f32_e32 v217, v217
	v_exp_f32_e32 v218, v218
	v_exp_f32_e32 v219, v219
	v_exp_f32_e32 v220, v220
	v_exp_f32_e32 v221, v221
	v_exp_f32_e32 v222, v222
	v_exp_f32_e32 v223, v223
	v_exp_f32_e32 v224, v224
	v_exp_f32_e32 v225, v225
	v_exp_f32_e32 v226, v226
	v_exp_f32_e32 v227, v227
	v_exp_f32_e32 v228, v228
	v_exp_f32_e32 v229, v229
	v_pk_add_f32 v[214:215], v[214:215], 1.0 op_sel_hi:[1,0]
	v_pk_add_f32 v[216:217], v[216:217], 1.0 op_sel_hi:[1,0]
	v_pk_add_f32 v[218:219], v[218:219], 1.0 op_sel_hi:[1,0]
	v_pk_add_f32 v[220:221], v[220:221], 1.0 op_sel_hi:[1,0]
	v_pk_add_f32 v[222:223], v[222:223], 1.0 op_sel_hi:[1,0]
	v_pk_add_f32 v[224:225], v[224:225], 1.0 op_sel_hi:[1,0]
	v_pk_add_f32 v[226:227], v[226:227], 1.0 op_sel_hi:[1,0]
	v_pk_add_f32 v[228:229], v[228:229], 1.0 op_sel_hi:[1,0]
	v_min_f32_e32 v214, 0x7149f2ca, v214
	v_min_f32_e32 v215, 0x7149f2ca, v215
	v_min_f32_e32 v216, 0x7149f2ca, v216
	v_min_f32_e32 v217, 0x7149f2ca, v217
	v_min_f32_e32 v218, 0x7149f2ca, v218
	v_min_f32_e32 v219, 0x7149f2ca, v219
	v_min_f32_e32 v220, 0x7149f2ca, v220
	v_min_f32_e32 v221, 0x7149f2ca, v221
	v_min_f32_e32 v222, 0x7149f2ca, v222
	v_min_f32_e32 v223, 0x7149f2ca, v223
	v_min_f32_e32 v224, 0x7149f2ca, v224
	v_min_f32_e32 v225, 0x7149f2ca, v225
	v_min_f32_e32 v226, 0x7149f2ca, v226
	v_min_f32_e32 v227, 0x7149f2ca, v227
	v_min_f32_e32 v228, 0x7149f2ca, v228
	v_min_f32_e32 v229, 0x7149f2ca, v229
	v_rcp_f32_e32 v230, v214
	v_rcp_f32_e32 v231, v215
	v_rcp_f32_e32 v232, v216
	v_rcp_f32_e32 v233, v217
	v_rcp_f32_e32 v234, v218
	v_rcp_f32_e32 v235, v219
	v_rcp_f32_e32 v236, v220
	v_rcp_f32_e32 v237, v221
	v_rcp_f32_e32 v238, v222
	v_rcp_f32_e32 v239, v223
	v_rcp_f32_e32 v240, v224
	v_rcp_f32_e32 v241, v225
	v_rcp_f32_e32 v242, v226
	v_rcp_f32_e32 v243, v227
	v_rcp_f32_e32 v244, v228
	v_rcp_f32_e32 v245, v229
	v_pk_mul_f32 v[230:231], v[230:231], v[218:219]
	v_pk_mul_f32 v[232:233], v[232:233], v[220:221]
	v_pk_mul_f32 v[234:235], v[234:235], v[222:223]
	v_pk_mul_f32 v[236:237], v[236:237], v[224:225]
	v_pk_mul_f32 v[238:239], v[238:239], v[226:227]
	v_pk_mul_f32 v[240:241], v[240:241], v[228:229]
	v_cvt_pk_bf16_f32 v174, v230, v231
	v_cvt_pk_bf16_f32 v175, v232, v233
	v_cvt_pk_bf16_f32 v178, v234, v235
	v_cvt_pk_bf16_f32 v179, v236, v237
	v_cvt_pk_bf16_f32 v182, v238, v239
	v_cvt_pk_bf16_f32 v183, v240, v241
	v_cvt_pk_bf16_f32 v186, v242, v243
	v_cvt_pk_bf16_f32 v187, v244, v245
	s_mov_b64 s[42:43], s[6:7]
	s_nop 1
	v_permlane16_swap_b32 v172, v174
	v_permlane16_swap_b32 v173, v175
	v_permlane16_swap_b32 v176, v178
	v_permlane16_swap_b32 v177, v179
	v_permlane16_swap_b32 v180, v182
	v_permlane16_swap_b32 v181, v183
	v_permlane16_swap_b32 v184, v186
	v_permlane16_swap_b32 v185, v187
	s_add_u32 s10, s42, s20
	s_addc_u32 s11, s43, s21
	v_lshl_add_u64 v[188:189], s[10:11], 0, v[168:169]
	global_store_dwordx4 v[188:189], v[172:175], off
	s_add_u32 s10, s42, s48
	s_addc_u32 s11, s43, s49
	v_lshl_add_u64 v[246:247], s[10:11], 0, v[168:169]
	global_store_dwordx4 v[246:247], v[176:179], off
	s_add_u32 s10, s42, s54
	s_addc_u32 s11, s43, s55
	v_lshl_add_u64 v[188:189], s[10:11], 0, v[168:169]
	global_store_dwordx4 v[188:189], v[180:183], off
	s_add_u32 s10, s42, s64
	s_addc_u32 s11, s43, s65
	v_lshl_add_u64 v[246:247], s[10:11], 0, v[168:169]
	global_store_dwordx4 v[246:247], v[184:187], off
	v_pk_add_f32 v[214:215], v[92:93], v[128:129]
	v_pk_add_f32 v[216:217], v[94:95], v[130:131]
	v_pk_add_f32 v[218:219], v[88:89], v[140:141]
	v_pk_add_f32 v[220:221], v[90:91], v[142:143]
	v_pk_add_f32 v[222:223], v[84:85], v[136:137]
	v_pk_add_f32 v[224:225], v[86:87], v[138:139]
	v_pk_add_f32 v[226:227], v[80:81], v[132:133]
	v_pk_add_f32 v[228:229], v[82:83], v[134:135]
	v_pk_mul_f32 v[214:215], v[214:215], s[8:9] op_sel_hi:[1,0]
	v_pk_mul_f32 v[216:217], v[216:217], s[8:9] op_sel_hi:[1,0]
	v_pk_mul_f32 v[218:219], v[218:219], s[8:9] op_sel_hi:[1,0]
	v_pk_mul_f32 v[220:221], v[220:221], s[8:9] op_sel_hi:[1,0]
	v_pk_mul_f32 v[222:223], v[222:223], s[8:9] op_sel_hi:[1,0]
	v_pk_mul_f32 v[224:225], v[224:225], s[8:9] op_sel_hi:[1,0]
	v_pk_mul_f32 v[226:227], v[226:227], s[8:9] op_sel_hi:[1,0]
	v_pk_mul_f32 v[228:229], v[228:229], s[8:9] op_sel_hi:[1,0]
	v_exp_f32_e32 v214, v214
	v_exp_f32_e32 v215, v215
	v_exp_f32_e32 v216, v216
	v_exp_f32_e32 v217, v217
	v_exp_f32_e32 v218, v218
	v_exp_f32_e32 v219, v219
	v_exp_f32_e32 v220, v220
	v_exp_f32_e32 v221, v221
	v_exp_f32_e32 v222, v222
	v_exp_f32_e32 v223, v223
	v_exp_f32_e32 v224, v224
	v_exp_f32_e32 v225, v225
	v_exp_f32_e32 v226, v226
	v_exp_f32_e32 v227, v227
	v_exp_f32_e32 v228, v228
	v_exp_f32_e32 v229, v229
	v_pk_add_f32 v[214:215], v[214:215], 1.0 op_sel_hi:[1,0]
	v_pk_add_f32 v[216:217], v[216:217], 1.0 op_sel_hi:[1,0]
	v_pk_add_f32 v[218:219], v[218:219], 1.0 op_sel_hi:[1,0]
	v_pk_add_f32 v[220:221], v[220:221], 1.0 op_sel_hi:[1,0]
	v_pk_add_f32 v[222:223], v[222:223], 1.0 op_sel_hi:[1,0]
	v_pk_add_f32 v[224:225], v[224:225], 1.0 op_sel_hi:[1,0]
	v_pk_add_f32 v[226:227], v[226:227], 1.0 op_sel_hi:[1,0]
	v_pk_add_f32 v[228:229], v[228:229], 1.0 op_sel_hi:[1,0]
	v_min_f32_e32 v214, 0x7149f2ca, v214
	v_min_f32_e32 v215, 0x7149f2ca, v215
	v_min_f32_e32 v216, 0x7149f2ca, v216
	v_min_f32_e32 v217, 0x7149f2ca, v217
	v_min_f32_e32 v218, 0x7149f2ca, v218
	v_min_f32_e32 v219, 0x7149f2ca, v219
	v_min_f32_e32 v220, 0x7149f2ca, v220
	v_min_f32_e32 v221, 0x7149f2ca, v221
	v_min_f32_e32 v222, 0x7149f2ca, v222
	v_min_f32_e32 v223, 0x7149f2ca, v223
; __device__ __forceinline__ unsigned cvt_pk_bf16(float lo, float hi) { const f32x2_t f = {lo, hi}; const bf16x2_t b = __builtin_convertvector(f, bf16x2_t); unsigned r; __builtin_memcpy(&r, &b, 4); return r; }
;     __device__ __forceinline__ void operator()(const Acc& acc, const Unit& u, int wr, int wc, int fr, int fq) const {
;     ...
;             for (int ai = 0; ai < 2; ++ai)
; #pragma unroll
;                 for (int m = 0; m < 4; ++m) { const int row = row0 + ai * 128 + m * 16; f32x4 g[4], d[4];
;                     const int cl = ch0 & 255, rl = row & 255;
;                     const size_t roff = ((((((size_t)((row >> 8) * 8 + (ch0 >> 8)) * 2 + (rl >> 7)) * 4 + ((rl >> 4) & 3)) * 2 + (cl >> 7)) * 8 + (((rl >> 6) & 1) * 4 + ((cl >> 5) & 3))) * 64
;                                          + ((rl & 15) + 16 * ((cl >> 3) & 3))) * 8 + (cl & 7);
; #pragma unroll
;                     for (int br = 0; br < 4; ++br)
; #pragma unroll
;                         for (int j = 0; j < 4; ++j) { d[br][j] = fminf(1.0f + __builtin_amdgcn_exp2f(-1.4426950408889634f * (acc[ai][br >> 1][m][br & 1][j] + bgv[br][j])), 1e30f); g[br][j] = __builtin_amdgcn_rcpf(d[br][j]); }
; #pragma unroll
;                     for (int k = 0; k < 4; ++k) { f32x4 r = g[k];
;                         if (k < 3) {
; #pragma unroll
;                             for (int j = 0; j < 4; ++j) r[j] = g[k][j] * d[k + 1][j]; }
;                         uint2 w; w.x = cvt_pk_bf16(r[0], r[1]); w.y = cvt_pk_bf16(r[2], r[3]);
;                         *(uint2*)(R + (size_t)k * T * DM + roff) = w; } }
	v_min_f32_e32 v224, 0x7149f2ca, v224
	v_min_f32_e32 v225, 0x7149f2ca, v225
	v_min_f32_e32 v226, 0x7149f2ca, v226
	v_min_f32_e32 v227, 0x7149f2ca, v227
	v_min_f32_e32 v228, 0x7149f2ca, v228
	v_min_f32_e32 v229, 0x7149f2ca, v229
	v_rcp_f32_e32 v230, v214
	v_rcp_f32_e32 v231, v215
	v_rcp_f32_e32 v232, v216
	v_rcp_f32_e32 v233, v217
	v_rcp_f32_e32 v234, v218
	v_rcp_f32_e32 v235, v219
	v_rcp_f32_e32 v236, v220
	v_rcp_f32_e32 v237, v221
	v_rcp_f32_e32 v238, v222
	v_rcp_f32_e32 v239, v223
	v_rcp_f32_e32 v240, v224
	v_rcp_f32_e32 v241, v225
	v_rcp_f32_e32 v242, v226
	v_rcp_f32_e32 v243, v227
	v_rcp_f32_e32 v244, v228
	v_rcp_f32_e32 v245, v229
	v_pk_mul_f32 v[230:231], v[230:231], v[218:219]
	v_pk_mul_f32 v[232:233], v[232:233], v[220:221]
	v_pk_mul_f32 v[234:235], v[234:235], v[222:223]
	v_pk_mul_f32 v[236:237], v[236:237], v[224:225]
	v_pk_mul_f32 v[238:239], v[238:239], v[226:227]
	v_pk_mul_f32 v[240:241], v[240:241], v[228:229]
	v_cvt_pk_bf16_f32 v172, v230, v231
	v_cvt_pk_bf16_f32 v173, v232, v233
	v_cvt_pk_bf16_f32 v176, v234, v235
	v_cvt_pk_bf16_f32 v177, v236, v237
	v_cvt_pk_bf16_f32 v180, v238, v239
	v_cvt_pk_bf16_f32 v181, v240, v241
	v_cvt_pk_bf16_f32 v184, v242, v243
	v_cvt_pk_bf16_f32 v185, v244, v245
	v_pk_add_f32 v[214:215], v[76:77], v[128:129]
	v_pk_add_f32 v[216:217], v[78:79], v[130:131]
	v_pk_add_f32 v[218:219], v[72:73], v[140:141]
	v_pk_add_f32 v[220:221], v[74:75], v[142:143]
	v_pk_add_f32 v[222:223], v[68:69], v[136:137]
	v_pk_add_f32 v[224:225], v[70:71], v[138:139]
	v_pk_add_f32 v[226:227], v[64:65], v[132:133]
	v_pk_add_f32 v[228:229], v[66:67], v[134:135]
	v_pk_mul_f32 v[214:215], v[214:215], s[8:9] op_sel_hi:[1,0]
	v_pk_mul_f32 v[216:217], v[216:217], s[8:9] op_sel_hi:[1,0]
	v_pk_mul_f32 v[218:219], v[218:219], s[8:9] op_sel_hi:[1,0]
	v_pk_mul_f32 v[220:221], v[220:221], s[8:9] op_sel_hi:[1,0]
	v_pk_mul_f32 v[222:223], v[222:223], s[8:9] op_sel_hi:[1,0]
	v_pk_mul_f32 v[224:225], v[224:225], s[8:9] op_sel_hi:[1,0]
	v_pk_mul_f32 v[226:227], v[226:227], s[8:9] op_sel_hi:[1,0]
	v_pk_mul_f32 v[228:229], v[228:229], s[8:9] op_sel_hi:[1,0]
	v_exp_f32_e32 v214, v214
	v_exp_f32_e32 v215, v215
	v_exp_f32_e32 v216, v216
	v_exp_f32_e32 v217, v217
	v_exp_f32_e32 v218, v218
	v_exp_f32_e32 v219, v219
	v_exp_f32_e32 v220, v220
	v_exp_f32_e32 v221, v221
	v_exp_f32_e32 v222, v222
	v_exp_f32_e32 v223, v223
	v_exp_f32_e32 v224, v224
	v_exp_f32_e32 v225, v225
	v_exp_f32_e32 v226, v226
	v_exp_f32_e32 v227, v227
	v_exp_f32_e32 v228, v228
	v_exp_f32_e32 v229, v229
	v_pk_add_f32 v[214:215], v[214:215], 1.0 op_sel_hi:[1,0]
	v_pk_add_f32 v[216:217], v[216:217], 1.0 op_sel_hi:[1,0]
	v_pk_add_f32 v[218:219], v[218:219], 1.0 op_sel_hi:[1,0]
	v_pk_add_f32 v[220:221], v[220:221], 1.0 op_sel_hi:[1,0]
	v_pk_add_f32 v[222:223], v[222:223], 1.0 op_sel_hi:[1,0]
	v_pk_add_f32 v[224:225], v[224:225], 1.0 op_sel_hi:[1,0]
	v_pk_add_f32 v[226:227], v[226:227], 1.0 op_sel_hi:[1,0]
	v_pk_add_f32 v[228:229], v[228:229], 1.0 op_sel_hi:[1,0]
	v_min_f32_e32 v214, 0x7149f2ca, v214
	v_min_f32_e32 v215, 0x7149f2ca, v215
	v_min_f32_e32 v216, 0x7149f2ca, v216
	v_min_f32_e32 v217, 0x7149f2ca, v217
	v_min_f32_e32 v218, 0x7149f2ca, v218
	v_min_f32_e32 v219, 0x7149f2ca, v219
	v_min_f32_e32 v220, 0x7149f2ca, v220
	v_min_f32_e32 v221, 0x7149f2ca, v221
	v_min_f32_e32 v222, 0x7149f2ca, v222
	v_min_f32_e32 v223, 0x7149f2ca, v223
	v_min_f32_e32 v224, 0x7149f2ca, v224
	v_min_f32_e32 v225, 0x7149f2ca, v225
	v_min_f32_e32 v226, 0x7149f2ca, v226
	v_min_f32_e32 v227, 0x7149f2ca, v227
	v_min_f32_e32 v228, 0x7149f2ca, v228
	v_min_f32_e32 v229, 0x7149f2ca, v229
	v_rcp_f32_e32 v230, v214
	v_rcp_f32_e32 v231, v215
	v_rcp_f32_e32 v232, v216
	v_rcp_f32_e32 v233, v217
	v_rcp_f32_e32 v234, v218
	v_rcp_f32_e32 v235, v219
	v_rcp_f32_e32 v236, v220
	v_rcp_f32_e32 v237, v221
	v_rcp_f32_e32 v238, v222
	v_rcp_f32_e32 v239, v223
	v_rcp_f32_e32 v240, v224
	v_rcp_f32_e32 v241, v225
	v_rcp_f32_e32 v242, v226
	v_rcp_f32_e32 v243, v227
	v_rcp_f32_e32 v244, v228
	v_rcp_f32_e32 v245, v229
	v_pk_mul_f32 v[230:231], v[230:231], v[218:219]
	v_pk_mul_f32 v[232:233], v[232:233], v[220:221]
	v_pk_mul_f32 v[234:235], v[234:235], v[222:223]
	v_pk_mul_f32 v[236:237], v[236:237], v[224:225]
	v_pk_mul_f32 v[238:239], v[238:239], v[226:227]
	v_pk_mul_f32 v[240:241], v[240:241], v[228:229]
	v_cvt_pk_bf16_f32 v174, v230, v231
	v_cvt_pk_bf16_f32 v175, v232, v233
	v_cvt_pk_bf16_f32 v178, v234, v235
	v_cvt_pk_bf16_f32 v179, v236, v237
	v_cvt_pk_bf16_f32 v182, v238, v239
	v_cvt_pk_bf16_f32 v183, v240, v241
	v_cvt_pk_bf16_f32 v186, v242, v243
	v_cvt_pk_bf16_f32 v187, v244, v245
	s_add_u32 s42, s6, 0x8000
	s_addc_u32 s43, s7, 0
	s_nop 1
	v_permlane16_swap_b32 v172, v174
	v_permlane16_swap_b32 v173, v175
	v_permlane16_swap_b32 v176, v178
	v_permlane16_swap_b32 v177, v179
	v_permlane16_swap_b32 v180, v182
	v_permlane16_swap_b32 v181, v183
	v_permlane16_swap_b32 v184, v186
	v_permlane16_swap_b32 v185, v187
	s_add_u32 s10, s42, s20
	s_addc_u32 s11, s43, s21
	v_lshl_add_u64 v[188:189], s[10:11], 0, v[168:169]
	global_store_dwordx4 v[188:189], v[172:175], off
	s_add_u32 s10, s42, s48
	s_addc_u32 s11, s43, s49
	v_lshl_add_u64 v[246:247], s[10:11], 0, v[168:169]
	global_store_dwordx4 v[246:247], v[176:179], off
	s_add_u32 s10, s42, s54
	s_addc_u32 s11, s43, s55
	v_lshl_add_u64 v[188:189], s[10:11], 0, v[168:169]
	global_store_dwordx4 v[188:189], v[180:183], off
	s_add_u32 s10, s42, s64
	s_addc_u32 s11, s43, s65
	v_lshl_add_u64 v[246:247], s[10:11], 0, v[168:169]
	global_store_dwordx4 v[246:247], v[184:187], off
	v_pk_add_f32 v[214:215], v[60:61], v[128:129]
	v_pk_add_f32 v[216:217], v[62:63], v[130:131]
	v_pk_add_f32 v[218:219], v[56:57], v[140:141]
; __device__ __forceinline__ unsigned cvt_pk_bf16(float lo, float hi) { const f32x2_t f = {lo, hi}; const bf16x2_t b = __builtin_convertvector(f, bf16x2_t); unsigned r; __builtin_memcpy(&r, &b, 4); return r; }
;     __device__ __forceinline__ void operator()(const Acc& acc, const Unit& u, int wr, int wc, int fr, int fq) const {
;     ...
;             for (int ai = 0; ai < 2; ++ai)
; #pragma unroll
;                 for (int m = 0; m < 4; ++m) { const int row = row0 + ai * 128 + m * 16; f32x4 g[4], d[4];
;                     const int cl = ch0 & 255, rl = row & 255;
;                     const size_t roff = ((((((size_t)((row >> 8) * 8 + (ch0 >> 8)) * 2 + (rl >> 7)) * 4 + ((rl >> 4) & 3)) * 2 + (cl >> 7)) * 8 + (((rl >> 6) & 1) * 4 + ((cl >> 5) & 3))) * 64
;                                          + ((rl & 15) + 16 * ((cl >> 3) & 3))) * 8 + (cl & 7);
; #pragma unroll
;                     for (int br = 0; br < 4; ++br)
; #pragma unroll
;                         for (int j = 0; j < 4; ++j) { d[br][j] = fminf(1.0f + __builtin_amdgcn_exp2f(-1.4426950408889634f * (acc[ai][br >> 1][m][br & 1][j] + bgv[br][j])), 1e30f); g[br][j] = __builtin_amdgcn_rcpf(d[br][j]); }
; #pragma unroll
;                     for (int k = 0; k < 4; ++k) { f32x4 r = g[k];
;                         if (k < 3) {
; #pragma unroll
;                             for (int j = 0; j < 4; ++j) r[j] = g[k][j] * d[k + 1][j]; }
;                         uint2 w; w.x = cvt_pk_bf16(r[0], r[1]); w.y = cvt_pk_bf16(r[2], r[3]);
;                         *(uint2*)(R + (size_t)k * T * DM + roff) = w; } }
	v_pk_add_f32 v[220:221], v[58:59], v[142:143]
	v_pk_add_f32 v[222:223], v[52:53], v[136:137]
	v_pk_add_f32 v[224:225], v[54:55], v[138:139]
	v_pk_add_f32 v[226:227], v[48:49], v[132:133]
	v_pk_add_f32 v[228:229], v[50:51], v[134:135]
	v_pk_mul_f32 v[214:215], v[214:215], s[8:9] op_sel_hi:[1,0]
	v_pk_mul_f32 v[216:217], v[216:217], s[8:9] op_sel_hi:[1,0]
	v_pk_mul_f32 v[218:219], v[218:219], s[8:9] op_sel_hi:[1,0]
	v_pk_mul_f32 v[220:221], v[220:221], s[8:9] op_sel_hi:[1,0]
	v_pk_mul_f32 v[222:223], v[222:223], s[8:9] op_sel_hi:[1,0]
	v_pk_mul_f32 v[224:225], v[224:225], s[8:9] op_sel_hi:[1,0]
	v_pk_mul_f32 v[226:227], v[226:227], s[8:9] op_sel_hi:[1,0]
	v_pk_mul_f32 v[228:229], v[228:229], s[8:9] op_sel_hi:[1,0]
	v_exp_f32_e32 v214, v214
	v_exp_f32_e32 v215, v215
	v_exp_f32_e32 v216, v216
	v_exp_f32_e32 v217, v217
	v_exp_f32_e32 v218, v218
	v_exp_f32_e32 v219, v219
	v_exp_f32_e32 v220, v220
	v_exp_f32_e32 v221, v221
	v_exp_f32_e32 v222, v222
	v_exp_f32_e32 v223, v223
	v_exp_f32_e32 v224, v224
	v_exp_f32_e32 v225, v225
	v_exp_f32_e32 v226, v226
	v_exp_f32_e32 v227, v227
	v_exp_f32_e32 v228, v228
	v_exp_f32_e32 v229, v229
	v_pk_add_f32 v[214:215], v[214:215], 1.0 op_sel_hi:[1,0]
	v_pk_add_f32 v[216:217], v[216:217], 1.0 op_sel_hi:[1,0]
	v_pk_add_f32 v[218:219], v[218:219], 1.0 op_sel_hi:[1,0]
	v_pk_add_f32 v[220:221], v[220:221], 1.0 op_sel_hi:[1,0]
	v_pk_add_f32 v[222:223], v[222:223], 1.0 op_sel_hi:[1,0]
	v_pk_add_f32 v[224:225], v[224:225], 1.0 op_sel_hi:[1,0]
	v_pk_add_f32 v[226:227], v[226:227], 1.0 op_sel_hi:[1,0]
	v_pk_add_f32 v[228:229], v[228:229], 1.0 op_sel_hi:[1,0]
	v_min_f32_e32 v214, 0x7149f2ca, v214
	v_min_f32_e32 v215, 0x7149f2ca, v215
	v_min_f32_e32 v216, 0x7149f2ca, v216
	v_min_f32_e32 v217, 0x7149f2ca, v217
	v_min_f32_e32 v218, 0x7149f2ca, v218
	v_min_f32_e32 v219, 0x7149f2ca, v219
	v_min_f32_e32 v220, 0x7149f2ca, v220
	v_min_f32_e32 v221, 0x7149f2ca, v221
	v_min_f32_e32 v222, 0x7149f2ca, v222
	v_min_f32_e32 v223, 0x7149f2ca, v223
	v_min_f32_e32 v224, 0x7149f2ca, v224
	v_min_f32_e32 v225, 0x7149f2ca, v225
	v_min_f32_e32 v226, 0x7149f2ca, v226
	v_min_f32_e32 v227, 0x7149f2ca, v227
	v_min_f32_e32 v228, 0x7149f2ca, v228
	v_min_f32_e32 v229, 0x7149f2ca, v229
	v_rcp_f32_e32 v230, v214
	v_rcp_f32_e32 v231, v215
	v_rcp_f32_e32 v232, v216
	v_rcp_f32_e32 v233, v217
	v_rcp_f32_e32 v234, v218
	v_rcp_f32_e32 v235, v219
	v_rcp_f32_e32 v236, v220
	v_rcp_f32_e32 v237, v221
	v_rcp_f32_e32 v238, v222
	v_rcp_f32_e32 v239, v223
	v_rcp_f32_e32 v240, v224
	v_rcp_f32_e32 v241, v225
	v_rcp_f32_e32 v242, v226
	v_rcp_f32_e32 v243, v227
	v_rcp_f32_e32 v244, v228
	v_rcp_f32_e32 v245, v229
	v_pk_mul_f32 v[230:231], v[230:231], v[218:219]
	v_pk_mul_f32 v[232:233], v[232:233], v[220:221]
	v_pk_mul_f32 v[234:235], v[234:235], v[222:223]
	v_pk_mul_f32 v[236:237], v[236:237], v[224:225]
	v_pk_mul_f32 v[238:239], v[238:239], v[226:227]
	v_pk_mul_f32 v[240:241], v[240:241], v[228:229]
	v_cvt_pk_bf16_f32 v172, v230, v231
	v_cvt_pk_bf16_f32 v173, v232, v233
	v_cvt_pk_bf16_f32 v176, v234, v235
	v_cvt_pk_bf16_f32 v177, v236, v237
	v_cvt_pk_bf16_f32 v180, v238, v239
	v_cvt_pk_bf16_f32 v181, v240, v241
	v_cvt_pk_bf16_f32 v184, v242, v243
	v_cvt_pk_bf16_f32 v185, v244, v245
	v_pk_add_f32 v[214:215], v[44:45], v[128:129]
	v_pk_add_f32 v[216:217], v[46:47], v[130:131]
	v_pk_add_f32 v[218:219], v[40:41], v[140:141]
	v_pk_add_f32 v[220:221], v[42:43], v[142:143]
	v_pk_add_f32 v[222:223], v[36:37], v[136:137]
	v_pk_add_f32 v[224:225], v[38:39], v[138:139]
	v_pk_add_f32 v[226:227], v[32:33], v[132:133]
	v_pk_add_f32 v[228:229], v[34:35], v[134:135]
	v_pk_mul_f32 v[214:215], v[214:215], s[8:9] op_sel_hi:[1,0]
	v_pk_mul_f32 v[216:217], v[216:217], s[8:9] op_sel_hi:[1,0]
	v_pk_mul_f32 v[218:219], v[218:219], s[8:9] op_sel_hi:[1,0]
	v_pk_mul_f32 v[220:221], v[220:221], s[8:9] op_sel_hi:[1,0]
	v_pk_mul_f32 v[222:223], v[222:223], s[8:9] op_sel_hi:[1,0]
	v_pk_mul_f32 v[224:225], v[224:225], s[8:9] op_sel_hi:[1,0]
	v_pk_mul_f32 v[226:227], v[226:227], s[8:9] op_sel_hi:[1,0]
	v_pk_mul_f32 v[228:229], v[228:229], s[8:9] op_sel_hi:[1,0]
	v_exp_f32_e32 v214, v214
	v_exp_f32_e32 v215, v215
	v_exp_f32_e32 v216, v216
	v_exp_f32_e32 v217, v217
	v_exp_f32_e32 v218, v218
	v_exp_f32_e32 v219, v219
	v_exp_f32_e32 v220, v220
	v_exp_f32_e32 v221, v221
	v_exp_f32_e32 v222, v222
	v_exp_f32_e32 v223, v223
	v_exp_f32_e32 v224, v224
	v_exp_f32_e32 v225, v225
	v_exp_f32_e32 v226, v226
	v_exp_f32_e32 v227, v227
	v_exp_f32_e32 v228, v228
	v_exp_f32_e32 v229, v229
	v_pk_add_f32 v[214:215], v[214:215], 1.0 op_sel_hi:[1,0]
	v_pk_add_f32 v[216:217], v[216:217], 1.0 op_sel_hi:[1,0]
	v_pk_add_f32 v[218:219], v[218:219], 1.0 op_sel_hi:[1,0]
	v_pk_add_f32 v[220:221], v[220:221], 1.0 op_sel_hi:[1,0]
	v_pk_add_f32 v[222:223], v[222:223], 1.0 op_sel_hi:[1,0]
	v_pk_add_f32 v[224:225], v[224:225], 1.0 op_sel_hi:[1,0]
	v_pk_add_f32 v[226:227], v[226:227], 1.0 op_sel_hi:[1,0]
	v_pk_add_f32 v[228:229], v[228:229], 1.0 op_sel_hi:[1,0]
	v_min_f32_e32 v214, 0x7149f2ca, v214
	v_min_f32_e32 v215, 0x7149f2ca, v215
	v_min_f32_e32 v216, 0x7149f2ca, v216
	v_min_f32_e32 v217, 0x7149f2ca, v217
	v_min_f32_e32 v218, 0x7149f2ca, v218
	v_min_f32_e32 v219, 0x7149f2ca, v219
	v_min_f32_e32 v220, 0x7149f2ca, v220
	v_min_f32_e32 v221, 0x7149f2ca, v221
	v_min_f32_e32 v222, 0x7149f2ca, v222
	v_min_f32_e32 v223, 0x7149f2ca, v223
	v_min_f32_e32 v224, 0x7149f2ca, v224
	v_min_f32_e32 v225, 0x7149f2ca, v225
	v_min_f32_e32 v226, 0x7149f2ca, v226
	v_min_f32_e32 v227, 0x7149f2ca, v227
	v_min_f32_e32 v228, 0x7149f2ca, v228
	v_min_f32_e32 v229, 0x7149f2ca, v229
	v_rcp_f32_e32 v230, v214
	v_rcp_f32_e32 v231, v215
	v_rcp_f32_e32 v232, v216
; __device__ __forceinline__ unsigned cvt_pk_bf16(float lo, float hi) { const f32x2_t f = {lo, hi}; const bf16x2_t b = __builtin_convertvector(f, bf16x2_t); unsigned r; __builtin_memcpy(&r, &b, 4); return r; }
;     __device__ __forceinline__ void operator()(const Acc& acc, const Unit& u, int wr, int wc, int fr, int fq) const {
;     ...
;             for (int ai = 0; ai < 2; ++ai)
; #pragma unroll
;                 for (int m = 0; m < 4; ++m) { const int row = row0 + ai * 128 + m * 16; f32x4 g[4], d[4];
;                     const int cl = ch0 & 255, rl = row & 255;
;                     const size_t roff = ((((((size_t)((row >> 8) * 8 + (ch0 >> 8)) * 2 + (rl >> 7)) * 4 + ((rl >> 4) & 3)) * 2 + (cl >> 7)) * 8 + (((rl >> 6) & 1) * 4 + ((cl >> 5) & 3))) * 64
;                                          + ((rl & 15) + 16 * ((cl >> 3) & 3))) * 8 + (cl & 7);
; #pragma unroll
;                     for (int br = 0; br < 4; ++br)
; #pragma unroll
;                         for (int j = 0; j < 4; ++j) { d[br][j] = fminf(1.0f + __builtin_amdgcn_exp2f(-1.4426950408889634f * (acc[ai][br >> 1][m][br & 1][j] + bgv[br][j])), 1e30f); g[br][j] = __builtin_amdgcn_rcpf(d[br][j]); }
; #pragma unroll
;                     for (int k = 0; k < 4; ++k) { f32x4 r = g[k];
;                         if (k < 3) {
; #pragma unroll
;                             for (int j = 0; j < 4; ++j) r[j] = g[k][j] * d[k + 1][j]; }
;                         uint2 w; w.x = cvt_pk_bf16(r[0], r[1]); w.y = cvt_pk_bf16(r[2], r[3]);
;                         *(uint2*)(R + (size_t)k * T * DM + roff) = w; } }
	v_rcp_f32_e32 v233, v217
	v_rcp_f32_e32 v234, v218
	v_rcp_f32_e32 v235, v219
	v_rcp_f32_e32 v236, v220
	v_rcp_f32_e32 v237, v221
	v_rcp_f32_e32 v238, v222
	v_rcp_f32_e32 v239, v223
	v_rcp_f32_e32 v240, v224
	v_rcp_f32_e32 v241, v225
	v_rcp_f32_e32 v242, v226
	v_rcp_f32_e32 v243, v227
	v_rcp_f32_e32 v244, v228
	v_rcp_f32_e32 v245, v229
	v_pk_mul_f32 v[230:231], v[230:231], v[218:219]
	v_pk_mul_f32 v[232:233], v[232:233], v[220:221]
	v_pk_mul_f32 v[234:235], v[234:235], v[222:223]
	v_pk_mul_f32 v[236:237], v[236:237], v[224:225]
	v_pk_mul_f32 v[238:239], v[238:239], v[226:227]
	v_pk_mul_f32 v[240:241], v[240:241], v[228:229]
	v_cvt_pk_bf16_f32 v174, v230, v231
	v_cvt_pk_bf16_f32 v175, v232, v233
	v_cvt_pk_bf16_f32 v178, v234, v235
	v_cvt_pk_bf16_f32 v179, v236, v237
	v_cvt_pk_bf16_f32 v182, v238, v239
	v_cvt_pk_bf16_f32 v183, v240, v241
	v_cvt_pk_bf16_f32 v186, v242, v243
	v_cvt_pk_bf16_f32 v187, v244, v245
	s_add_u32 s42, s6, 0x10000
	s_addc_u32 s43, s7, 0
	s_nop 1
	v_permlane16_swap_b32 v172, v174
	v_permlane16_swap_b32 v173, v175
	v_permlane16_swap_b32 v176, v178
	v_permlane16_swap_b32 v177, v179
	v_permlane16_swap_b32 v180, v182
	v_permlane16_swap_b32 v181, v183
	v_permlane16_swap_b32 v184, v186
	v_permlane16_swap_b32 v185, v187
	s_add_u32 s10, s42, s20
	s_addc_u32 s11, s43, s21
	v_lshl_add_u64 v[188:189], s[10:11], 0, v[168:169]
	global_store_dwordx4 v[188:189], v[172:175], off
	s_add_u32 s10, s42, s48
	s_addc_u32 s11, s43, s49
	v_lshl_add_u64 v[246:247], s[10:11], 0, v[168:169]
	global_store_dwordx4 v[246:247], v[176:179], off
	s_add_u32 s10, s42, s54
	s_addc_u32 s11, s43, s55
	v_lshl_add_u64 v[188:189], s[10:11], 0, v[168:169]
	global_store_dwordx4 v[188:189], v[180:183], off
	s_add_u32 s10, s42, s64
	s_addc_u32 s11, s43, s65
	v_lshl_add_u64 v[246:247], s[10:11], 0, v[168:169]
	global_store_dwordx4 v[246:247], v[184:187], off
	v_pk_add_f32 v[214:215], v[28:29], v[128:129]
	v_pk_add_f32 v[216:217], v[30:31], v[130:131]
	v_pk_add_f32 v[218:219], v[24:25], v[140:141]
	v_pk_add_f32 v[220:221], v[26:27], v[142:143]
	v_pk_add_f32 v[222:223], v[20:21], v[136:137]
	v_pk_add_f32 v[224:225], v[22:23], v[138:139]
	v_pk_add_f32 v[226:227], v[16:17], v[132:133]
	v_pk_add_f32 v[228:229], v[18:19], v[134:135]
	v_pk_mul_f32 v[214:215], v[214:215], s[8:9] op_sel_hi:[1,0]
	v_pk_mul_f32 v[216:217], v[216:217], s[8:9] op_sel_hi:[1,0]
	v_pk_mul_f32 v[218:219], v[218:219], s[8:9] op_sel_hi:[1,0]
	v_pk_mul_f32 v[220:221], v[220:221], s[8:9] op_sel_hi:[1,0]
	v_pk_mul_f32 v[222:223], v[222:223], s[8:9] op_sel_hi:[1,0]
	v_pk_mul_f32 v[224:225], v[224:225], s[8:9] op_sel_hi:[1,0]
	v_pk_mul_f32 v[226:227], v[226:227], s[8:9] op_sel_hi:[1,0]
	v_pk_mul_f32 v[228:229], v[228:229], s[8:9] op_sel_hi:[1,0]
	v_exp_f32_e32 v214, v214
	v_exp_f32_e32 v215, v215
	v_exp_f32_e32 v216, v216
	v_exp_f32_e32 v217, v217
	v_exp_f32_e32 v218, v218
	v_exp_f32_e32 v219, v219
	v_exp_f32_e32 v220, v220
	v_exp_f32_e32 v221, v221
	v_exp_f32_e32 v222, v222
	v_exp_f32_e32 v223, v223
	v_exp_f32_e32 v224, v224
	v_exp_f32_e32 v225, v225
	v_exp_f32_e32 v226, v226
	v_exp_f32_e32 v227, v227
	v_exp_f32_e32 v228, v228
	v_exp_f32_e32 v229, v229
	v_pk_add_f32 v[214:215], v[214:215], 1.0 op_sel_hi:[1,0]
	v_pk_add_f32 v[216:217], v[216:217], 1.0 op_sel_hi:[1,0]
	v_pk_add_f32 v[218:219], v[218:219], 1.0 op_sel_hi:[1,0]
	v_pk_add_f32 v[220:221], v[220:221], 1.0 op_sel_hi:[1,0]
	v_pk_add_f32 v[222:223], v[222:223], 1.0 op_sel_hi:[1,0]
	v_pk_add_f32 v[224:225], v[224:225], 1.0 op_sel_hi:[1,0]
	v_pk_add_f32 v[226:227], v[226:227], 1.0 op_sel_hi:[1,0]
	v_pk_add_f32 v[228:229], v[228:229], 1.0 op_sel_hi:[1,0]
	v_min_f32_e32 v214, 0x7149f2ca, v214
	v_min_f32_e32 v215, 0x7149f2ca, v215
	v_min_f32_e32 v216, 0x7149f2ca, v216
	v_min_f32_e32 v217, 0x7149f2ca, v217
	v_min_f32_e32 v218, 0x7149f2ca, v218
	v_min_f32_e32 v219, 0x7149f2ca, v219
	v_min_f32_e32 v220, 0x7149f2ca, v220
	v_min_f32_e32 v221, 0x7149f2ca, v221
	v_min_f32_e32 v222, 0x7149f2ca, v222
	v_min_f32_e32 v223, 0x7149f2ca, v223
	v_min_f32_e32 v224, 0x7149f2ca, v224
	v_min_f32_e32 v225, 0x7149f2ca, v225
	v_min_f32_e32 v226, 0x7149f2ca, v226
	v_min_f32_e32 v227, 0x7149f2ca, v227
	v_min_f32_e32 v228, 0x7149f2ca, v228
	v_min_f32_e32 v229, 0x7149f2ca, v229
	v_rcp_f32_e32 v230, v214
	v_rcp_f32_e32 v231, v215
	v_rcp_f32_e32 v232, v216
	v_rcp_f32_e32 v233, v217
	v_rcp_f32_e32 v234, v218
	v_rcp_f32_e32 v235, v219
	v_rcp_f32_e32 v236, v220
	v_rcp_f32_e32 v237, v221
	v_rcp_f32_e32 v238, v222
	v_rcp_f32_e32 v239, v223
	v_rcp_f32_e32 v240, v224
	v_rcp_f32_e32 v241, v225
	v_rcp_f32_e32 v242, v226
	v_rcp_f32_e32 v243, v227
	v_rcp_f32_e32 v244, v228
	v_rcp_f32_e32 v245, v229
	v_pk_mul_f32 v[230:231], v[230:231], v[218:219]
	v_pk_mul_f32 v[232:233], v[232:233], v[220:221]
; __device__ __forceinline__ unsigned cvt_pk_bf16(float lo, float hi) { const f32x2_t f = {lo, hi}; const bf16x2_t b = __builtin_convertvector(f, bf16x2_t); unsigned r; __builtin_memcpy(&r, &b, 4); return r; }
;     __device__ __forceinline__ void operator()(const Acc& acc, const Unit& u, int wr, int wc, int fr, int fq) const {
;     ...
;             for (int ai = 0; ai < 2; ++ai)
; #pragma unroll
;                 for (int m = 0; m < 4; ++m) { const int row = row0 + ai * 128 + m * 16; f32x4 g[4], d[4];
;                     const int cl = ch0 & 255, rl = row & 255;
;                     const size_t roff = ((((((size_t)((row >> 8) * 8 + (ch0 >> 8)) * 2 + (rl >> 7)) * 4 + ((rl >> 4) & 3)) * 2 + (cl >> 7)) * 8 + (((rl >> 6) & 1) * 4 + ((cl >> 5) & 3))) * 64
;                                          + ((rl & 15) + 16 * ((cl >> 3) & 3))) * 8 + (cl & 7);
; #pragma unroll
;                     for (int br = 0; br < 4; ++br)
; #pragma unroll
;                         for (int j = 0; j < 4; ++j) { d[br][j] = fminf(1.0f + __builtin_amdgcn_exp2f(-1.4426950408889634f * (acc[ai][br >> 1][m][br & 1][j] + bgv[br][j])), 1e30f); g[br][j] = __builtin_amdgcn_rcpf(d[br][j]); }
; #pragma unroll
;                     for (int k = 0; k < 4; ++k) { f32x4 r = g[k];
;                         if (k < 3) {
; #pragma unroll
;                             for (int j = 0; j < 4; ++j) r[j] = g[k][j] * d[k + 1][j]; }
;                         uint2 w; w.x = cvt_pk_bf16(r[0], r[1]); w.y = cvt_pk_bf16(r[2], r[3]);
;                         *(uint2*)(R + (size_t)k * T * DM + roff) = w; } }
	v_pk_mul_f32 v[234:235], v[234:235], v[222:223]
	v_pk_mul_f32 v[236:237], v[236:237], v[224:225]
	v_pk_mul_f32 v[238:239], v[238:239], v[226:227]
	v_pk_mul_f32 v[240:241], v[240:241], v[228:229]
	v_cvt_pk_bf16_f32 v172, v230, v231
	v_cvt_pk_bf16_f32 v173, v232, v233
	v_cvt_pk_bf16_f32 v176, v234, v235
	v_cvt_pk_bf16_f32 v177, v236, v237
	v_cvt_pk_bf16_f32 v180, v238, v239
	v_cvt_pk_bf16_f32 v181, v240, v241
	v_cvt_pk_bf16_f32 v184, v242, v243
	v_cvt_pk_bf16_f32 v185, v244, v245
	v_pk_add_f32 v[214:215], v[12:13], v[128:129]
	v_pk_add_f32 v[216:217], v[14:15], v[130:131]
	v_pk_add_f32 v[218:219], v[8:9], v[140:141]
	v_pk_add_f32 v[220:221], v[10:11], v[142:143]
	v_pk_add_f32 v[222:223], v[4:5], v[136:137]
	v_pk_add_f32 v[224:225], v[6:7], v[138:139]
	v_pk_add_f32 v[226:227], v[0:1], v[132:133]
	v_pk_add_f32 v[228:229], v[2:3], v[134:135]
	v_pk_mul_f32 v[214:215], v[214:215], s[8:9] op_sel_hi:[1,0]
	v_pk_mul_f32 v[216:217], v[216:217], s[8:9] op_sel_hi:[1,0]
	v_pk_mul_f32 v[218:219], v[218:219], s[8:9] op_sel_hi:[1,0]
	v_pk_mul_f32 v[220:221], v[220:221], s[8:9] op_sel_hi:[1,0]
	v_pk_mul_f32 v[222:223], v[222:223], s[8:9] op_sel_hi:[1,0]
	v_pk_mul_f32 v[224:225], v[224:225], s[8:9] op_sel_hi:[1,0]
	v_pk_mul_f32 v[226:227], v[226:227], s[8:9] op_sel_hi:[1,0]
	v_pk_mul_f32 v[228:229], v[228:229], s[8:9] op_sel_hi:[1,0]
	v_exp_f32_e32 v214, v214
	v_exp_f32_e32 v215, v215
	v_exp_f32_e32 v216, v216
	v_exp_f32_e32 v217, v217
	v_exp_f32_e32 v218, v218
	v_exp_f32_e32 v219, v219
	v_exp_f32_e32 v220, v220
	v_exp_f32_e32 v221, v221
	v_exp_f32_e32 v222, v222
	v_exp_f32_e32 v223, v223
	v_exp_f32_e32 v224, v224
	v_exp_f32_e32 v225, v225
	v_exp_f32_e32 v226, v226
	v_exp_f32_e32 v227, v227
	v_exp_f32_e32 v228, v228
	v_exp_f32_e32 v229, v229
	v_pk_add_f32 v[214:215], v[214:215], 1.0 op_sel_hi:[1,0]
	v_pk_add_f32 v[216:217], v[216:217], 1.0 op_sel_hi:[1,0]
	v_pk_add_f32 v[218:219], v[218:219], 1.0 op_sel_hi:[1,0]
	v_pk_add_f32 v[220:221], v[220:221], 1.0 op_sel_hi:[1,0]
	v_pk_add_f32 v[222:223], v[222:223], 1.0 op_sel_hi:[1,0]
	v_pk_add_f32 v[224:225], v[224:225], 1.0 op_sel_hi:[1,0]
	v_pk_add_f32 v[226:227], v[226:227], 1.0 op_sel_hi:[1,0]
	v_pk_add_f32 v[228:229], v[228:229], 1.0 op_sel_hi:[1,0]
	v_min_f32_e32 v214, 0x7149f2ca, v214
	v_min_f32_e32 v215, 0x7149f2ca, v215
	v_min_f32_e32 v216, 0x7149f2ca, v216
	v_min_f32_e32 v217, 0x7149f2ca, v217
	v_min_f32_e32 v218, 0x7149f2ca, v218
	v_min_f32_e32 v219, 0x7149f2ca, v219
	v_min_f32_e32 v220, 0x7149f2ca, v220
	v_min_f32_e32 v221, 0x7149f2ca, v221
	v_min_f32_e32 v222, 0x7149f2ca, v222
	v_min_f32_e32 v223, 0x7149f2ca, v223
	v_min_f32_e32 v224, 0x7149f2ca, v224
	v_min_f32_e32 v225, 0x7149f2ca, v225
	v_min_f32_e32 v226, 0x7149f2ca, v226
	v_min_f32_e32 v227, 0x7149f2ca, v227
	v_min_f32_e32 v228, 0x7149f2ca, v228
	v_min_f32_e32 v229, 0x7149f2ca, v229
	v_rcp_f32_e32 v230, v214
	v_rcp_f32_e32 v231, v215
	v_rcp_f32_e32 v232, v216
	v_rcp_f32_e32 v233, v217
	v_rcp_f32_e32 v234, v218
	v_rcp_f32_e32 v235, v219
	v_rcp_f32_e32 v236, v220
	v_rcp_f32_e32 v237, v221
	v_rcp_f32_e32 v238, v222
	v_rcp_f32_e32 v239, v223
	v_rcp_f32_e32 v240, v224
	v_rcp_f32_e32 v241, v225
	v_rcp_f32_e32 v242, v226
	v_rcp_f32_e32 v243, v227
	v_rcp_f32_e32 v244, v228
	v_rcp_f32_e32 v245, v229
	v_pk_mul_f32 v[230:231], v[230:231], v[218:219]
	v_pk_mul_f32 v[232:233], v[232:233], v[220:221]
	v_pk_mul_f32 v[234:235], v[234:235], v[222:223]
	v_pk_mul_f32 v[236:237], v[236:237], v[224:225]
	v_pk_mul_f32 v[238:239], v[238:239], v[226:227]
	v_pk_mul_f32 v[240:241], v[240:241], v[228:229]
	v_cvt_pk_bf16_f32 v174, v230, v231
	v_cvt_pk_bf16_f32 v175, v232, v233
	v_cvt_pk_bf16_f32 v178, v234, v235
	v_cvt_pk_bf16_f32 v179, v236, v237
	v_cvt_pk_bf16_f32 v182, v238, v239
	v_cvt_pk_bf16_f32 v183, v240, v241
	v_cvt_pk_bf16_f32 v186, v242, v243
	v_cvt_pk_bf16_f32 v187, v244, v245
	s_add_u32 s42, s6, 0x18000
	s_addc_u32 s43, s7, 0
	s_nop 1
	v_permlane16_swap_b32 v172, v174
	v_permlane16_swap_b32 v173, v175
	v_permlane16_swap_b32 v176, v178
	v_permlane16_swap_b32 v177, v179
	v_permlane16_swap_b32 v180, v182
	v_permlane16_swap_b32 v181, v183
	v_permlane16_swap_b32 v184, v186
	v_permlane16_swap_b32 v185, v187
	s_add_u32 s10, s42, s20
	s_addc_u32 s11, s43, s21
	v_lshl_add_u64 v[188:189], s[10:11], 0, v[168:169]
	global_store_dwordx4 v[188:189], v[172:175], off
	s_add_u32 s10, s42, s48
	s_addc_u32 s11, s43, s49
	v_lshl_add_u64 v[246:247], s[10:11], 0, v[168:169]
	global_store_dwordx4 v[246:247], v[176:179], off
	s_add_u32 s10, s42, s54
	s_addc_u32 s11, s43, s55
	v_lshl_add_u64 v[188:189], s[10:11], 0, v[168:169]
	global_store_dwordx4 v[188:189], v[180:183], off
	s_add_u32 s10, s42, s64
	s_addc_u32 s11, s43, s65
	v_lshl_add_u64 v[246:247], s[10:11], 0, v[168:169]
	global_store_dwordx4 v[246:247], v[184:187], off
